# mlstm_a2 state scan: each trip touches the next trip's chunk states so its loads hit the L2 (cooperative L2 prefetch of a serial chain)
# baseline (speedup 1.0000x reference)
.LBB0_589:
	v_lshl_add_u64 v[58:59], v[54:55], 0, s[4:5]
	v_add_co_u32_e32 v76, vcc, 0x18e04000, v58
	v_lshl_add_u64 v[56:57], v[52:53], 0, s[4:5]
	s_nop 0
	v_addc_co_u32_e32 v77, vcc, 0, v59, vcc
	s_mov_b64 s[18:19], 0x1ae84000
	s_mov_b32 s8, 0x1ae85000
	v_lshl_add_u64 v[2:3], v[56:57], 0, s[18:19]
	v_add_co_u32_e32 v4, vcc, s8, v56
	s_mov_b64 s[18:19], 0x1ae85000
	s_nop 0
	v_addc_co_u32_e32 v5, vcc, 0, v57, vcc
	v_lshl_add_u64 v[10:11], v[56:57], 0, s[18:19]
	s_mov_b32 s8, 0x18e0c000
	global_load_dwordx4 v[46:49], v[76:77], off
	global_load_dwordx4 v[30:33], v[4:5], off offset:-4096
	global_load_dwordx4 v[26:29], v[4:5], off
	global_load_dwordx4 v[6:9], v[2:3], off offset:16
	s_nop 0
	global_load_dwordx4 v[2:5], v[10:11], off offset:16
	v_add_co_u32_e32 v10, vcc, s8, v58
	s_mov_b32 s8, 0x18e14000
	s_nop 0
	v_addc_co_u32_e32 v11, vcc, 0, v59, vcc
	v_add_co_u32_e32 v12, vcc, s8, v58
	s_mov_b32 s8, 0x18e1c000
	s_nop 0
	v_addc_co_u32_e32 v13, vcc, 0, v59, vcc
	global_load_dwordx4 v[42:45], v[10:11], off
	global_load_dwordx4 v[38:41], v[12:13], off
	v_add_co_u32_e32 v10, vcc, s8, v58
	s_mov_b32 s8, 0x18e24000
	s_nop 0
	v_addc_co_u32_e32 v11, vcc, 0, v59, vcc
	v_add_co_u32_e32 v12, vcc, s8, v58
	s_mov_b32 s8, 0x18e2c000
	s_nop 0
	v_addc_co_u32_e32 v13, vcc, 0, v59, vcc
	global_load_dwordx4 v[34:37], v[10:11], off
	global_load_dwordx4 v[22:25], v[12:13], off
	v_add_co_u32_e32 v10, vcc, s8, v58
	s_mov_b32 s8, 0x18e34000
	s_nop 0
	v_addc_co_u32_e32 v11, vcc, 0, v59, vcc
	v_add_co_u32_e32 v12, vcc, s8, v58
	s_mov_b32 s8, 0x18e3c000
	s_nop 0
	v_addc_co_u32_e32 v13, vcc, 0, v59, vcc
	global_load_dwordx4 v[18:21], v[10:11], off
	global_load_dwordx4 v[14:17], v[12:13], off
	v_add_co_u32_e32 v10, vcc, s8, v58
	v_cvt_pk_bf16_f32 v72, v62, v63
	s_nop 0
	v_addc_co_u32_e32 v11, vcc, 0, v59, vcc
	global_load_dwordx4 v[10:13], v[10:11], off
	s_cmp_ge_i32 s2, 16
	s_cbranch_scc1 .La2t_skip
	v_add_co_u32_e32 v96, vcc, 0x18e44000, v58
	s_nop 1
	v_addc_co_u32_e32 v97, vcc, 0, v59, vcc
	global_load_dword v98, v[96:97], off
	v_add_co_u32_e32 v96, vcc, 0x18e4c000, v58
	s_nop 1
	v_addc_co_u32_e32 v97, vcc, 0, v59, vcc
	global_load_dword v98, v[96:97], off
	v_add_co_u32_e32 v96, vcc, 0x18e54000, v58
	s_nop 1
	v_addc_co_u32_e32 v97, vcc, 0, v59, vcc
	global_load_dword v98, v[96:97], off
	v_add_co_u32_e32 v96, vcc, 0x18e5c000, v58
	s_nop 1
	v_addc_co_u32_e32 v97, vcc, 0, v59, vcc
	global_load_dword v98, v[96:97], off
	v_add_co_u32_e32 v96, vcc, 0x18e64000, v58
	s_nop 1
	v_addc_co_u32_e32 v97, vcc, 0, v59, vcc
	global_load_dword v98, v[96:97], off
	v_add_co_u32_e32 v96, vcc, 0x18e6c000, v58
	s_nop 1
	v_addc_co_u32_e32 v97, vcc, 0, v59, vcc
	global_load_dword v98, v[96:97], off
	v_add_co_u32_e32 v96, vcc, 0x18e74000, v58
	s_nop 1
	v_addc_co_u32_e32 v97, vcc, 0, v59, vcc
	global_load_dword v98, v[96:97], off
	v_add_co_u32_e32 v96, vcc, 0x18e7c000, v58
	s_nop 1
	v_addc_co_u32_e32 v97, vcc, 0, v59, vcc
	global_load_dword v98, v[96:97], off
.La2t_skip:
	v_cvt_pk_bf16_f32 v73, v64, v65
	v_cvt_pk_bf16_f32 v74, v66, v67
	v_cvt_pk_bf16_f32 v75, v60, v61
	global_store_dwordx4 v[76:77], v[72:75], off
	s_and_saveexec_b64 s[42:43], s[0:1]
	s_cbranch_execz .LBB0_591
	v_add_co_u32_e32 v72, vcc, 0x1ae86000, v56
	s_nop 1
	v_addc_co_u32_e32 v73, vcc, 0, v57, vcc
	global_store_dword v[72:73], v0, off
